# np18 + nt cache policy on the read-once loads of the o_b transpose phase
# speedup vs baseline: 1.0260x; 1.0014x over previous
.LBB0_1012:
	s_and_b32 s8, s14, 0xffffffc0
	v_add_u32_e32 v18, s8, v8
	v_ashrrev_i32_e32 v19, 31, v18
	s_and_b32 s9, s10, 0x3f00
	v_lshlrev_b64 v[18:19], 15, v[18:19]
	s_lshl_b32 s4, s9, 1
	v_lshl_add_u64 v[18:19], s[64:65], 0, v[18:19]
	v_lshl_add_u64 v[18:19], v[18:19], 0, s[4:5]
	v_lshl_add_u64 v[34:35], v[18:19], 0, v[6:7]
	global_load_dwordx4 v[18:21], v[34:35], off nt
	global_load_dwordx4 v[22:25], v[34:35], off offset:128 nt
	global_load_dwordx4 v[26:29], v[34:35], off offset:256 nt
	global_load_dwordx4 v[30:33], v[34:35], off offset:384 nt
	v_or_b32_e32 v2, s9, v8
	s_ashr_i32 s9, s8, 31
	v_lshl_add_u64 v[34:35], s[8:9], 1, v[4:5]
	v_lshlrev_b32_e32 v2, 11, v2
	v_lshl_add_u64 v[34:35], v[34:35], 0, v[2:3]
	v_add_co_u32_e32 v36, vcc, s12, v34
	s_add_i32 s14, s14, s70
	s_nop 0
	v_addc_co_u32_e32 v37, vcc, 0, v35, vcc
	v_add_co_u32_e32 v38, vcc, s13, v34
	s_add_i32 s10, s10, s11
	s_nop 0
	v_addc_co_u32_e32 v39, vcc, 0, v35, vcc
	s_cmpk_lt_i32 s14, 0x400
	v_add_co_u32_e32 v40, vcc, 0x60000, v34
	s_waitcnt vmcnt(0)
	ds_write2_b32 v10, v18, v19 offset1:1
	ds_write2_b32 v10, v20, v21 offset0:2 offset1:3
	ds_write2_b32 v11, v22, v23 offset1:1
	ds_write2_b32 v12, v24, v25 offset1:1
	ds_write2_b32 v13, v26, v27 offset1:1
	ds_write2_b32 v14, v28, v29 offset1:1
	ds_write2_b32 v15, v30, v31 offset1:1
	ds_write2_b32 v16, v32, v33 offset1:1
	s_waitcnt lgkmcnt(0)
	s_barrier
	ds_read_u16 v2, v9
	ds_read_u16 v17, v9 offset:132
	ds_read_u16 v19, v9 offset:264
	ds_read_u16 v20, v9 offset:396
	ds_read_u16 v21, v9 offset:528
	ds_read_u16 v22, v9 offset:660
	ds_read_u16 v23, v9 offset:792
	ds_read_u16 v24, v9 offset:924
	ds_read_u16 v25, v9 offset:8448
	ds_read_u16 v26, v9 offset:8580
	ds_read_u16 v27, v9 offset:8712
	ds_read_u16 v28, v9 offset:8844
	ds_read_u16 v29, v9 offset:8976
	ds_read_u16 v30, v9 offset:9108
	ds_read_u16 v31, v9 offset:9240
	ds_read_u16 v32, v9 offset:9372
	ds_read_u16 v33, v9 offset:16896
	ds_read_u16 v42, v9 offset:17028
	ds_read_u16 v43, v9 offset:17160
	ds_read_u16 v44, v9 offset:17292
	ds_read_u16 v45, v9 offset:17424
	ds_read_u16 v46, v9 offset:17556
	ds_read_u16 v47, v9 offset:17688
	ds_read_u16 v48, v9 offset:17820
	ds_read_u16 v49, v9 offset:25344
	ds_read_u16 v50, v9 offset:25476
	ds_read_u16 v51, v9 offset:25608
	ds_read_u16 v52, v9 offset:25740
	ds_read_u16 v53, v9 offset:25872
	ds_read_u16 v54, v9 offset:26004
	ds_read_u16 v55, v9 offset:26136
	ds_read_u16 v56, v9 offset:26268
	s_waitcnt lgkmcnt(14)
	v_lshl_or_b32 v18, v17, 16, v2
	v_lshl_or_b32 v19, v20, 16, v19
	v_lshl_or_b32 v20, v22, 16, v21
	v_lshl_or_b32 v21, v24, 16, v23
	v_addc_co_u32_e32 v41, vcc, 0, v35, vcc
	v_lshl_or_b32 v22, v26, 16, v25
	v_lshl_or_b32 v23, v28, 16, v27
	v_lshl_or_b32 v24, v30, 16, v29
	v_lshl_or_b32 v25, v32, 16, v31
	v_lshl_or_b32 v26, v42, 16, v33
	s_waitcnt lgkmcnt(12)
	v_lshl_or_b32 v27, v44, 16, v43
	s_waitcnt lgkmcnt(10)
	v_lshl_or_b32 v28, v46, 16, v45
	s_waitcnt lgkmcnt(8)
	v_lshl_or_b32 v29, v48, 16, v47
	s_waitcnt lgkmcnt(6)
	v_lshl_or_b32 v30, v50, 16, v49
	s_waitcnt lgkmcnt(4)
	v_lshl_or_b32 v31, v52, 16, v51
	s_waitcnt lgkmcnt(2)
	v_lshl_or_b32 v32, v54, 16, v53
	s_waitcnt lgkmcnt(0)
	v_lshl_or_b32 v33, v56, 16, v55
	global_store_dwordx4 v[34:35], v[18:21], off
	global_store_dwordx4 v[36:37], v[22:25], off
	global_store_dwordx4 v[38:39], v[26:29], off
	global_store_dwordx4 v[40:41], v[30:33], off
	s_barrier
	s_cbranch_scc1 .LBB0_1012
